# finalize first stage: all 30 token-shift row loads issued up front (hand-written), alignment-preserving pads
# speedup vs baseline: 1.0089x; 1.0089x over previous
.LBB0_452:
	s_waitcnt vmcnt(0)
	s_and_b32 s3, s78, 63
	s_ashr_i32 s28, s78, 6
	s_lshl_b32 s0, s3, 6
	s_lshl_b32 s1, s28, 12
	v_readlane_b32 s30, v253, 60
	v_add_u32_e32 v228, s84, v1
	v_and_b32_e32 v229, 7, v1
	v_ashrrev_i32_e32 v228, 3, v228
	v_add_u32_e32 v230, s0, v228
	v_add_u32_e32 v231, s1, v230
	v_lshlrev_b32_e32 v232, 9, v231
	v_lshl_add_u32 v232, v229, 5, v232
	v_add_u32_e32 v232, 0x7c00100, v232
	v_lshlrev_b32_e32 v233, 10, v231
	v_lshl_add_u32 v233, v229, 4, v233
	v_add_u32_e32 v233, 0x6c00000, v233
	global_load_dwordx4 v[2:5], v232, s[72:73]
	global_load_dwordx4 v[6:9], v232, s[72:73] offset:16
	global_load_dwordx4 v[58:61], v233, s[72:73]
	global_load_dwordx4 v[62:65], v233, s[72:73] offset:128
	global_load_dwordx4 v[66:69], v233, s[72:73] offset:256
	global_load_dwordx4 v[70:73], v233, s[72:73] offset:384
	global_load_dwordx4 v[74:77], v233, s[72:73] offset:512
	global_load_dwordx4 v[78:81], v233, s[72:73] offset:640
	global_load_dwordx4 v[82:85], v233, s[72:73] offset:768
	global_load_dwordx4 v[86:89], v233, s[72:73] offset:896
	s_movk_i32 s29, 0xfff
	v_cmp_lt_i32_e64 s[36:37], 0, v230
	v_cmp_gt_i32_e64 s[38:39], s29, v230
	v_lshlrev_b32_e32 v234, 6, v229
	v_lshlrev_b32_e32 v235, 5, v229
	v_add_u32_e32 v235, 0x1000, v235
	s_and_b64 s[56:57], s[36:37], s[38:39]
	s_cmp_eq_u64 s[56:57], exec
	s_cbranch_scc1 .Lfin_rows_nz
	v_mov_b32_e32 v10, 0
	v_mov_b32_e32 v11, 0
	v_mov_b32_e32 v12, 0
	v_mov_b32_e32 v13, 0
	v_mov_b32_e32 v14, 0
	v_mov_b32_e32 v15, 0
	v_mov_b32_e32 v16, 0
	v_mov_b32_e32 v17, 0
	v_mov_b32_e32 v18, 0
	v_mov_b32_e32 v19, 0
	v_mov_b32_e32 v20, 0
	v_mov_b32_e32 v21, 0
	v_mov_b32_e32 v22, 0
	v_mov_b32_e32 v23, 0
	v_mov_b32_e32 v24, 0
	v_mov_b32_e32 v25, 0
	v_mov_b32_e32 v90, 0
	v_mov_b32_e32 v91, 0
	v_mov_b32_e32 v92, 0
	v_mov_b32_e32 v93, 0
	v_mov_b32_e32 v94, 0
	v_mov_b32_e32 v95, 0
	v_mov_b32_e32 v96, 0
	v_mov_b32_e32 v97, 0
	v_mov_b32_e32 v98, 0
	v_mov_b32_e32 v99, 0
	v_mov_b32_e32 v100, 0
	v_mov_b32_e32 v101, 0
	v_mov_b32_e32 v102, 0
	v_mov_b32_e32 v103, 0
	v_mov_b32_e32 v104, 0
	v_mov_b32_e32 v105, 0
	v_mov_b32_e32 v106, 0
	v_mov_b32_e32 v107, 0
	v_mov_b32_e32 v108, 0
	v_mov_b32_e32 v109, 0
	v_mov_b32_e32 v110, 0
	v_mov_b32_e32 v111, 0
	v_mov_b32_e32 v112, 0
	v_mov_b32_e32 v113, 0
	v_mov_b32_e32 v114, 0
	v_mov_b32_e32 v115, 0
	v_mov_b32_e32 v116, 0
	v_mov_b32_e32 v117, 0
	v_mov_b32_e32 v118, 0
	v_mov_b32_e32 v119, 0
	v_mov_b32_e32 v120, 0
	v_mov_b32_e32 v121, 0
	v_mov_b32_e32 v122, 0
	v_mov_b32_e32 v123, 0
	v_mov_b32_e32 v124, 0
	v_mov_b32_e32 v125, 0
	v_mov_b32_e32 v126, 0
	v_mov_b32_e32 v127, 0
	v_mov_b32_e32 v128, 0
	v_mov_b32_e32 v129, 0
	v_mov_b32_e32 v130, 0
	v_mov_b32_e32 v131, 0
	v_mov_b32_e32 v132, 0
	v_mov_b32_e32 v133, 0
	v_mov_b32_e32 v134, 0
	v_mov_b32_e32 v135, 0
	v_mov_b32_e32 v136, 0
	v_mov_b32_e32 v137, 0
	v_mov_b32_e32 v138, 0
	v_mov_b32_e32 v139, 0
	v_mov_b32_e32 v140, 0
	v_mov_b32_e32 v141, 0
	v_mov_b32_e32 v142, 0
	v_mov_b32_e32 v143, 0
	v_mov_b32_e32 v144, 0
	v_mov_b32_e32 v145, 0
	v_mov_b32_e32 v146, 0
	v_mov_b32_e32 v147, 0
	v_mov_b32_e32 v148, 0
	v_mov_b32_e32 v149, 0
	v_mov_b32_e32 v150, 0
	v_mov_b32_e32 v151, 0
	v_mov_b32_e32 v152, 0
	v_mov_b32_e32 v153, 0
.Lfin_rows_nz:
	s_mov_b64 s[56:57], exec
	s_and_b64 exec, s[56:57], s[36:37]
	global_load_dwordx4 v[10:13], v232, s[72:73] offset:-512
	global_load_dwordx4 v[14:17], v232, s[72:73] offset:-496
	global_load_dwordx4 v[90:93], v233, s[72:73] offset:-1024
	global_load_dwordx4 v[94:97], v233, s[72:73] offset:-896
	global_load_dwordx4 v[98:101], v233, s[72:73] offset:-768
	global_load_dwordx4 v[102:105], v233, s[72:73] offset:-640
	global_load_dwordx4 v[106:109], v233, s[72:73] offset:-512
	global_load_dwordx4 v[110:113], v233, s[72:73] offset:-384
	global_load_dwordx4 v[114:117], v233, s[72:73] offset:-256
	global_load_dwordx4 v[118:121], v233, s[72:73] offset:-128
	s_and_b64 exec, s[56:57], s[38:39]
	global_load_dwordx4 v[18:21], v232, s[72:73] offset:512
	global_load_dwordx4 v[22:25], v232, s[72:73] offset:528
	global_load_dwordx4 v[122:125], v233, s[72:73] offset:1024
	global_load_dwordx4 v[126:129], v233, s[72:73] offset:1152
	global_load_dwordx4 v[130:133], v233, s[72:73] offset:1280
	global_load_dwordx4 v[134:137], v233, s[72:73] offset:1408
	global_load_dwordx4 v[138:141], v233, s[72:73] offset:1536
	global_load_dwordx4 v[142:145], v233, s[72:73] offset:1664
	global_load_dwordx4 v[146:149], v233, s[72:73] offset:1792
	global_load_dwordx4 v[150:153], v233, s[72:73] offset:1920
	s_mov_b64 exec, s[56:57]
	global_load_dwordx4 v[26:29], v234, s[94:95]
	global_load_dwordx4 v[30:33], v234, s[94:95] offset:16
	global_load_dwordx4 v[34:37], v234, s[94:95] offset:32
	global_load_dwordx4 v[38:41], v234, s[94:95] offset:48
	global_load_dwordx4 v[42:45], v234, s[24:25]
	global_load_dwordx4 v[46:49], v234, s[24:25] offset:16
	global_load_dwordx4 v[50:53], v234, s[24:25] offset:32
	global_load_dwordx4 v[54:57], v234, s[24:25] offset:48
	global_load_dwordx4 v[154:157], v235, s[54:55]
	global_load_dwordx4 v[158:161], v235, s[54:55] offset:16
	global_load_dwordx4 v[162:165], v235, s[58:59]
	global_load_dwordx4 v[166:169], v235, s[58:59] offset:16
	global_load_dwordx4 v[170:173], v235, s[54:55] offset:256
	global_load_dwordx4 v[174:177], v235, s[54:55] offset:272
	global_load_dwordx4 v[178:181], v235, s[58:59] offset:256
	global_load_dwordx4 v[182:185], v235, s[58:59] offset:272
	s_movk_i32 s29, 0x110
	v_mul_lo_u32 v236, v228, s29
	v_lshl_add_u32 v236, v229, 5, v236
	s_movk_i32 s29, 0x410
	v_mul_lo_u32 v237, v228, s29
	v_lshl_add_u32 v237, v229, 4, v237
	v_add_u32_e32 v237, s30, v237
	s_waitcnt vmcnt(8)
	v_lshlrev_b32_e32 v196, 16, v2
	v_and_b32_e32 v197, 0xffff0000, v2
	v_lshlrev_b32_e32 v198, 16, v10
	v_and_b32_e32 v199, 0xffff0000, v10
	v_lshlrev_b32_e32 v200, 16, v18
	v_and_b32_e32 v201, 0xffff0000, v18
	v_lshlrev_b32_e32 v202, 16, v3
	v_and_b32_e32 v203, 0xffff0000, v3
	v_lshlrev_b32_e32 v204, 16, v11
	v_and_b32_e32 v205, 0xffff0000, v11
	v_lshlrev_b32_e32 v206, 16, v19
	v_and_b32_e32 v207, 0xffff0000, v19
	v_lshlrev_b32_e32 v208, 16, v4
	v_and_b32_e32 v209, 0xffff0000, v4
	v_lshlrev_b32_e32 v210, 16, v12
	v_and_b32_e32 v211, 0xffff0000, v12
	v_lshlrev_b32_e32 v212, 16, v20
	v_and_b32_e32 v213, 0xffff0000, v20
	v_lshlrev_b32_e32 v214, 16, v5
	v_and_b32_e32 v215, 0xffff0000, v5
	v_lshlrev_b32_e32 v216, 16, v13
	v_and_b32_e32 v217, 0xffff0000, v13
	v_lshlrev_b32_e32 v218, 16, v21
	v_and_b32_e32 v219, 0xffff0000, v21
	v_pk_add_f32 v[198:199], v[198:199], v[196:197] neg_lo:[0,1] neg_hi:[0,1]
	v_pk_add_f32 v[200:201], v[200:201], v[196:197] neg_lo:[0,1] neg_hi:[0,1]
	v_pk_add_f32 v[204:205], v[204:205], v[202:203] neg_lo:[0,1] neg_hi:[0,1]
	v_pk_add_f32 v[206:207], v[206:207], v[202:203] neg_lo:[0,1] neg_hi:[0,1]
	v_pk_add_f32 v[210:211], v[210:211], v[208:209] neg_lo:[0,1] neg_hi:[0,1]
	v_pk_add_f32 v[212:213], v[212:213], v[208:209] neg_lo:[0,1] neg_hi:[0,1]
	v_pk_add_f32 v[216:217], v[216:217], v[214:215] neg_lo:[0,1] neg_hi:[0,1]
	v_pk_add_f32 v[218:219], v[218:219], v[214:215] neg_lo:[0,1] neg_hi:[0,1]
	v_pk_fma_f32 v[196:197], v[198:199], v[26:27], v[196:197]
	v_pk_fma_f32 v[202:203], v[204:205], v[28:29], v[202:203]
	v_pk_fma_f32 v[208:209], v[210:211], v[30:31], v[208:209]
	v_pk_fma_f32 v[214:215], v[216:217], v[32:33], v[214:215]
	v_pk_fma_f32 v[196:197], v[200:201], v[42:43], v[196:197]
	v_pk_fma_f32 v[202:203], v[206:207], v[44:45], v[202:203]
	v_pk_fma_f32 v[208:209], v[212:213], v[46:47], v[208:209]
	v_pk_fma_f32 v[214:215], v[218:219], v[48:49], v[214:215]
	v_mul_f32_e32 v196, 0xbfb8aa3b, v196
	v_mul_f32_e32 v197, 0xbfb8aa3b, v197
	v_mul_f32_e32 v202, 0xbfb8aa3b, v202
	v_mul_f32_e32 v203, 0xbfb8aa3b, v203
	v_mul_f32_e32 v208, 0xbfb8aa3b, v208
	v_mul_f32_e32 v209, 0xbfb8aa3b, v209
	v_mul_f32_e32 v214, 0xbfb8aa3b, v214
	v_mul_f32_e32 v215, 0xbfb8aa3b, v215
	v_exp_f32_e32 v196, v196
	v_exp_f32_e32 v197, v197
	v_exp_f32_e32 v202, v202
	v_exp_f32_e32 v203, v203
	v_exp_f32_e32 v208, v208
	v_exp_f32_e32 v209, v209
	v_exp_f32_e32 v214, v214
	v_exp_f32_e32 v215, v215
	v_add_f32_e32 v196, 1.0, v196
	v_add_f32_e32 v197, 1.0, v197
	v_add_f32_e32 v202, 1.0, v202
	v_add_f32_e32 v203, 1.0, v203
	v_add_f32_e32 v208, 1.0, v208
	v_add_f32_e32 v209, 1.0, v209
	v_add_f32_e32 v214, 1.0, v214
	v_add_f32_e32 v215, 1.0, v215
	v_rcp_f32_e32 v196, v196
	v_rcp_f32_e32 v197, v197
	v_rcp_f32_e32 v202, v202
	v_rcp_f32_e32 v203, v203
	v_rcp_f32_e32 v208, v208
	v_rcp_f32_e32 v209, v209
	v_rcp_f32_e32 v214, v214
	v_rcp_f32_e32 v215, v215
	s_nop 0
	v_cvt_pk_bf16_f32 v2, v196, v197
	v_cvt_pk_bf16_f32 v3, v202, v203
	v_cvt_pk_bf16_f32 v4, v208, v209
	v_cvt_pk_bf16_f32 v5, v214, v215
	ds_write_b128 v236, v[2:5]
	v_lshlrev_b32_e32 v196, 16, v6
	v_and_b32_e32 v197, 0xffff0000, v6
	v_lshlrev_b32_e32 v198, 16, v14
	v_and_b32_e32 v199, 0xffff0000, v14
	v_lshlrev_b32_e32 v200, 16, v22
	v_and_b32_e32 v201, 0xffff0000, v22
	v_lshlrev_b32_e32 v202, 16, v7
	v_and_b32_e32 v203, 0xffff0000, v7
	v_lshlrev_b32_e32 v204, 16, v15
	v_and_b32_e32 v205, 0xffff0000, v15
	v_lshlrev_b32_e32 v206, 16, v23
	v_and_b32_e32 v207, 0xffff0000, v23
	v_lshlrev_b32_e32 v208, 16, v8
	v_and_b32_e32 v209, 0xffff0000, v8
	v_lshlrev_b32_e32 v210, 16, v16
	v_and_b32_e32 v211, 0xffff0000, v16
	v_lshlrev_b32_e32 v212, 16, v24
	v_and_b32_e32 v213, 0xffff0000, v24
	v_lshlrev_b32_e32 v214, 16, v9
	v_and_b32_e32 v215, 0xffff0000, v9
	v_lshlrev_b32_e32 v216, 16, v17
	v_and_b32_e32 v217, 0xffff0000, v17
	v_lshlrev_b32_e32 v218, 16, v25
	v_and_b32_e32 v219, 0xffff0000, v25
	v_pk_add_f32 v[198:199], v[198:199], v[196:197] neg_lo:[0,1] neg_hi:[0,1]
	v_pk_add_f32 v[200:201], v[200:201], v[196:197] neg_lo:[0,1] neg_hi:[0,1]
	v_pk_add_f32 v[204:205], v[204:205], v[202:203] neg_lo:[0,1] neg_hi:[0,1]
	v_pk_add_f32 v[206:207], v[206:207], v[202:203] neg_lo:[0,1] neg_hi:[0,1]
	v_pk_add_f32 v[210:211], v[210:211], v[208:209] neg_lo:[0,1] neg_hi:[0,1]
	v_pk_add_f32 v[212:213], v[212:213], v[208:209] neg_lo:[0,1] neg_hi:[0,1]
	v_pk_add_f32 v[216:217], v[216:217], v[214:215] neg_lo:[0,1] neg_hi:[0,1]
	v_pk_add_f32 v[218:219], v[218:219], v[214:215] neg_lo:[0,1] neg_hi:[0,1]
	v_pk_fma_f32 v[196:197], v[198:199], v[34:35], v[196:197]
	v_pk_fma_f32 v[202:203], v[204:205], v[36:37], v[202:203]
	v_pk_fma_f32 v[208:209], v[210:211], v[38:39], v[208:209]
	v_pk_fma_f32 v[214:215], v[216:217], v[40:41], v[214:215]
	v_pk_fma_f32 v[196:197], v[200:201], v[50:51], v[196:197]
	v_pk_fma_f32 v[202:203], v[206:207], v[52:53], v[202:203]
	v_pk_fma_f32 v[208:209], v[212:213], v[54:55], v[208:209]
	v_pk_fma_f32 v[214:215], v[218:219], v[56:57], v[214:215]
	v_mul_f32_e32 v196, 0xbfb8aa3b, v196
	v_mul_f32_e32 v197, 0xbfb8aa3b, v197
	v_mul_f32_e32 v202, 0xbfb8aa3b, v202
	v_mul_f32_e32 v203, 0xbfb8aa3b, v203
	v_mul_f32_e32 v208, 0xbfb8aa3b, v208
	v_mul_f32_e32 v209, 0xbfb8aa3b, v209
	v_mul_f32_e32 v214, 0xbfb8aa3b, v214
	v_mul_f32_e32 v215, 0xbfb8aa3b, v215
	v_exp_f32_e32 v196, v196
	v_exp_f32_e32 v197, v197
	v_exp_f32_e32 v202, v202
	v_exp_f32_e32 v203, v203
	v_exp_f32_e32 v208, v208
	v_exp_f32_e32 v209, v209
	v_exp_f32_e32 v214, v214
	v_exp_f32_e32 v215, v215
	v_add_f32_e32 v196, 1.0, v196
	v_add_f32_e32 v197, 1.0, v197
	v_add_f32_e32 v202, 1.0, v202
	v_add_f32_e32 v203, 1.0, v203
	v_add_f32_e32 v208, 1.0, v208
	v_add_f32_e32 v209, 1.0, v209
	v_add_f32_e32 v214, 1.0, v214
	v_add_f32_e32 v215, 1.0, v215
	v_rcp_f32_e32 v196, v196
	v_rcp_f32_e32 v197, v197
	v_rcp_f32_e32 v202, v202
	v_rcp_f32_e32 v203, v203
	v_rcp_f32_e32 v208, v208
	v_rcp_f32_e32 v209, v209
	v_rcp_f32_e32 v214, v214
	v_rcp_f32_e32 v215, v215
	s_nop 0
	v_cvt_pk_bf16_f32 v6, v196, v197
	v_cvt_pk_bf16_f32 v7, v202, v203
	v_cvt_pk_bf16_f32 v8, v208, v209
	v_cvt_pk_bf16_f32 v9, v214, v215
	ds_write_b128 v236, v[6:9] offset:16
	global_load_dwordx4 v[2:5], v235, s[54:55] offset:512
	global_load_dwordx4 v[6:9], v235, s[54:55] offset:528
	global_load_dwordx4 v[10:13], v235, s[58:59] offset:512
	global_load_dwordx4 v[14:17], v235, s[58:59] offset:528
	global_load_dwordx4 v[18:21], v235, s[54:55] offset:768
	global_load_dwordx4 v[22:25], v235, s[54:55] offset:784
	global_load_dwordx4 v[26:29], v235, s[58:59] offset:768
	global_load_dwordx4 v[30:33], v235, s[58:59] offset:784
	global_load_dwordx4 v[34:37], v235, s[54:55] offset:1024
	global_load_dwordx4 v[38:41], v235, s[54:55] offset:1040
	global_load_dwordx4 v[42:45], v235, s[58:59] offset:1024
	global_load_dwordx4 v[46:49], v235, s[58:59] offset:1040
	s_waitcnt vmcnt(16)
	v_lshlrev_b32_e32 v196, 16, v58
	v_and_b32_e32 v197, 0xffff0000, v58
	v_lshlrev_b32_e32 v198, 16, v90
	v_and_b32_e32 v199, 0xffff0000, v90
	v_lshlrev_b32_e32 v200, 16, v122
	v_and_b32_e32 v201, 0xffff0000, v122
	v_lshlrev_b32_e32 v202, 16, v59
	v_and_b32_e32 v203, 0xffff0000, v59
	v_lshlrev_b32_e32 v204, 16, v91
	v_and_b32_e32 v205, 0xffff0000, v91
	v_lshlrev_b32_e32 v206, 16, v123
	v_and_b32_e32 v207, 0xffff0000, v123
	v_lshlrev_b32_e32 v208, 16, v60
	v_and_b32_e32 v209, 0xffff0000, v60
	v_lshlrev_b32_e32 v210, 16, v92
	v_and_b32_e32 v211, 0xffff0000, v92
	v_lshlrev_b32_e32 v212, 16, v124
	v_and_b32_e32 v213, 0xffff0000, v124
	v_lshlrev_b32_e32 v214, 16, v61
	v_and_b32_e32 v215, 0xffff0000, v61
	v_lshlrev_b32_e32 v216, 16, v93
	v_and_b32_e32 v217, 0xffff0000, v93
	v_lshlrev_b32_e32 v218, 16, v125
	v_and_b32_e32 v219, 0xffff0000, v125
	v_pk_add_f32 v[198:199], v[198:199], v[196:197] neg_lo:[0,1] neg_hi:[0,1]
	v_pk_add_f32 v[200:201], v[200:201], v[196:197] neg_lo:[0,1] neg_hi:[0,1]
	v_pk_add_f32 v[204:205], v[204:205], v[202:203] neg_lo:[0,1] neg_hi:[0,1]
	v_pk_add_f32 v[206:207], v[206:207], v[202:203] neg_lo:[0,1] neg_hi:[0,1]
	v_pk_add_f32 v[210:211], v[210:211], v[208:209] neg_lo:[0,1] neg_hi:[0,1]
	v_pk_add_f32 v[212:213], v[212:213], v[208:209] neg_lo:[0,1] neg_hi:[0,1]
	v_pk_add_f32 v[216:217], v[216:217], v[214:215] neg_lo:[0,1] neg_hi:[0,1]
	v_pk_add_f32 v[218:219], v[218:219], v[214:215] neg_lo:[0,1] neg_hi:[0,1]
	v_pk_fma_f32 v[196:197], v[198:199], v[154:155], v[196:197]
	v_pk_fma_f32 v[202:203], v[204:205], v[156:157], v[202:203]
	v_pk_fma_f32 v[208:209], v[210:211], v[158:159], v[208:209]
	v_pk_fma_f32 v[214:215], v[216:217], v[160:161], v[214:215]
	v_pk_fma_f32 v[196:197], v[200:201], v[162:163], v[196:197]
	v_pk_fma_f32 v[202:203], v[206:207], v[164:165], v[202:203]
	v_pk_fma_f32 v[208:209], v[212:213], v[166:167], v[208:209]
	v_pk_fma_f32 v[214:215], v[218:219], v[168:169], v[214:215]
	v_cvt_pk_bf16_f32 v58, v196, v197
	v_cvt_pk_bf16_f32 v59, v202, v203
	v_cvt_pk_bf16_f32 v60, v208, v209
	v_cvt_pk_bf16_f32 v61, v214, v215
	ds_write_b128 v237, v[58:61]
	s_waitcnt vmcnt(12)
	v_lshlrev_b32_e32 v196, 16, v62
	v_and_b32_e32 v197, 0xffff0000, v62
	v_lshlrev_b32_e32 v198, 16, v94
	v_and_b32_e32 v199, 0xffff0000, v94
	v_lshlrev_b32_e32 v200, 16, v126
	v_and_b32_e32 v201, 0xffff0000, v126
	v_lshlrev_b32_e32 v202, 16, v63
	v_and_b32_e32 v203, 0xffff0000, v63
	v_lshlrev_b32_e32 v204, 16, v95
	v_and_b32_e32 v205, 0xffff0000, v95
	v_lshlrev_b32_e32 v206, 16, v127
	v_and_b32_e32 v207, 0xffff0000, v127
	v_lshlrev_b32_e32 v208, 16, v64
	v_and_b32_e32 v209, 0xffff0000, v64
	v_lshlrev_b32_e32 v210, 16, v96
	v_and_b32_e32 v211, 0xffff0000, v96
	v_lshlrev_b32_e32 v212, 16, v128
	v_and_b32_e32 v213, 0xffff0000, v128
	v_lshlrev_b32_e32 v214, 16, v65
	v_and_b32_e32 v215, 0xffff0000, v65
	v_lshlrev_b32_e32 v216, 16, v97
	v_and_b32_e32 v217, 0xffff0000, v97
	v_lshlrev_b32_e32 v218, 16, v129
	v_and_b32_e32 v219, 0xffff0000, v129
	v_pk_add_f32 v[198:199], v[198:199], v[196:197] neg_lo:[0,1] neg_hi:[0,1]
	v_pk_add_f32 v[200:201], v[200:201], v[196:197] neg_lo:[0,1] neg_hi:[0,1]
	v_pk_add_f32 v[204:205], v[204:205], v[202:203] neg_lo:[0,1] neg_hi:[0,1]
	v_pk_add_f32 v[206:207], v[206:207], v[202:203] neg_lo:[0,1] neg_hi:[0,1]
	v_pk_add_f32 v[210:211], v[210:211], v[208:209] neg_lo:[0,1] neg_hi:[0,1]
	v_pk_add_f32 v[212:213], v[212:213], v[208:209] neg_lo:[0,1] neg_hi:[0,1]
	v_pk_add_f32 v[216:217], v[216:217], v[214:215] neg_lo:[0,1] neg_hi:[0,1]
	v_pk_add_f32 v[218:219], v[218:219], v[214:215] neg_lo:[0,1] neg_hi:[0,1]
	v_pk_fma_f32 v[196:197], v[198:199], v[170:171], v[196:197]
	v_pk_fma_f32 v[202:203], v[204:205], v[172:173], v[202:203]
	v_pk_fma_f32 v[208:209], v[210:211], v[174:175], v[208:209]
	v_pk_fma_f32 v[214:215], v[216:217], v[176:177], v[214:215]
	v_pk_fma_f32 v[196:197], v[200:201], v[178:179], v[196:197]
	v_pk_fma_f32 v[202:203], v[206:207], v[180:181], v[202:203]
	v_pk_fma_f32 v[208:209], v[212:213], v[182:183], v[208:209]
	v_pk_fma_f32 v[214:215], v[218:219], v[184:185], v[214:215]
	v_cvt_pk_bf16_f32 v62, v196, v197
	v_cvt_pk_bf16_f32 v63, v202, v203
	v_cvt_pk_bf16_f32 v64, v208, v209
	v_cvt_pk_bf16_f32 v65, v214, v215
	ds_write_b128 v237, v[62:65] offset:128
	global_load_dwordx4 v[154:157], v235, s[54:55] offset:1280
	global_load_dwordx4 v[158:161], v235, s[54:55] offset:1296
	global_load_dwordx4 v[162:165], v235, s[58:59] offset:1280
	global_load_dwordx4 v[166:169], v235, s[58:59] offset:1296
	global_load_dwordx4 v[170:173], v235, s[54:55] offset:1536
	global_load_dwordx4 v[174:177], v235, s[54:55] offset:1552
	global_load_dwordx4 v[178:181], v235, s[58:59] offset:1536
	global_load_dwordx4 v[182:185], v235, s[58:59] offset:1552
	global_load_dwordx4 v[90:93], v235, s[54:55] offset:1792
	global_load_dwordx4 v[94:97], v235, s[54:55] offset:1808
	global_load_dwordx4 v[122:125], v235, s[58:59] offset:1792
	global_load_dwordx4 v[126:129], v235, s[58:59] offset:1808
	s_waitcnt vmcnt(20)
	v_lshlrev_b32_e32 v196, 16, v66
	v_and_b32_e32 v197, 0xffff0000, v66
	v_lshlrev_b32_e32 v198, 16, v98
	v_and_b32_e32 v199, 0xffff0000, v98
	v_lshlrev_b32_e32 v200, 16, v130
	v_and_b32_e32 v201, 0xffff0000, v130
	v_lshlrev_b32_e32 v202, 16, v67
	v_and_b32_e32 v203, 0xffff0000, v67
	v_lshlrev_b32_e32 v204, 16, v99
	v_and_b32_e32 v205, 0xffff0000, v99
	v_lshlrev_b32_e32 v206, 16, v131
	v_and_b32_e32 v207, 0xffff0000, v131
	v_lshlrev_b32_e32 v208, 16, v68
	v_and_b32_e32 v209, 0xffff0000, v68
	v_lshlrev_b32_e32 v210, 16, v100
	v_and_b32_e32 v211, 0xffff0000, v100
	v_lshlrev_b32_e32 v212, 16, v132
	v_and_b32_e32 v213, 0xffff0000, v132
	v_lshlrev_b32_e32 v214, 16, v69
	v_and_b32_e32 v215, 0xffff0000, v69
	v_lshlrev_b32_e32 v216, 16, v101
	v_and_b32_e32 v217, 0xffff0000, v101
	v_lshlrev_b32_e32 v218, 16, v133
	v_and_b32_e32 v219, 0xffff0000, v133
	v_pk_add_f32 v[198:199], v[198:199], v[196:197] neg_lo:[0,1] neg_hi:[0,1]
	v_pk_add_f32 v[200:201], v[200:201], v[196:197] neg_lo:[0,1] neg_hi:[0,1]
	v_pk_add_f32 v[204:205], v[204:205], v[202:203] neg_lo:[0,1] neg_hi:[0,1]
	v_pk_add_f32 v[206:207], v[206:207], v[202:203] neg_lo:[0,1] neg_hi:[0,1]
	v_pk_add_f32 v[210:211], v[210:211], v[208:209] neg_lo:[0,1] neg_hi:[0,1]
	v_pk_add_f32 v[212:213], v[212:213], v[208:209] neg_lo:[0,1] neg_hi:[0,1]
	v_pk_add_f32 v[216:217], v[216:217], v[214:215] neg_lo:[0,1] neg_hi:[0,1]
	v_pk_add_f32 v[218:219], v[218:219], v[214:215] neg_lo:[0,1] neg_hi:[0,1]
	v_pk_fma_f32 v[196:197], v[198:199], v[2:3], v[196:197]
	v_pk_fma_f32 v[202:203], v[204:205], v[4:5], v[202:203]
	v_pk_fma_f32 v[208:209], v[210:211], v[6:7], v[208:209]
	v_pk_fma_f32 v[214:215], v[216:217], v[8:9], v[214:215]
	v_pk_fma_f32 v[196:197], v[200:201], v[10:11], v[196:197]
	v_pk_fma_f32 v[202:203], v[206:207], v[12:13], v[202:203]
	v_pk_fma_f32 v[208:209], v[212:213], v[14:15], v[208:209]
	v_pk_fma_f32 v[214:215], v[218:219], v[16:17], v[214:215]
	v_cvt_pk_bf16_f32 v66, v196, v197
	v_cvt_pk_bf16_f32 v67, v202, v203
	v_cvt_pk_bf16_f32 v68, v208, v209
	v_cvt_pk_bf16_f32 v69, v214, v215
	ds_write_b128 v237, v[66:69] offset:256
	s_waitcnt vmcnt(16)
	v_lshlrev_b32_e32 v196, 16, v70
	v_and_b32_e32 v197, 0xffff0000, v70
	v_lshlrev_b32_e32 v198, 16, v102
	v_and_b32_e32 v199, 0xffff0000, v102
	v_lshlrev_b32_e32 v200, 16, v134
	v_and_b32_e32 v201, 0xffff0000, v134
	v_lshlrev_b32_e32 v202, 16, v71
	v_and_b32_e32 v203, 0xffff0000, v71
	v_lshlrev_b32_e32 v204, 16, v103
	v_and_b32_e32 v205, 0xffff0000, v103
	v_lshlrev_b32_e32 v206, 16, v135
	v_and_b32_e32 v207, 0xffff0000, v135
	v_lshlrev_b32_e32 v208, 16, v72
	v_and_b32_e32 v209, 0xffff0000, v72
	v_lshlrev_b32_e32 v210, 16, v104
	v_and_b32_e32 v211, 0xffff0000, v104
	v_lshlrev_b32_e32 v212, 16, v136
	v_and_b32_e32 v213, 0xffff0000, v136
	v_lshlrev_b32_e32 v214, 16, v73
	v_and_b32_e32 v215, 0xffff0000, v73
	v_lshlrev_b32_e32 v216, 16, v105
	v_and_b32_e32 v217, 0xffff0000, v105
	v_lshlrev_b32_e32 v218, 16, v137
	v_and_b32_e32 v219, 0xffff0000, v137
	v_pk_add_f32 v[198:199], v[198:199], v[196:197] neg_lo:[0,1] neg_hi:[0,1]
	v_pk_add_f32 v[200:201], v[200:201], v[196:197] neg_lo:[0,1] neg_hi:[0,1]
	v_pk_add_f32 v[204:205], v[204:205], v[202:203] neg_lo:[0,1] neg_hi:[0,1]
	v_pk_add_f32 v[206:207], v[206:207], v[202:203] neg_lo:[0,1] neg_hi:[0,1]
	v_pk_add_f32 v[210:211], v[210:211], v[208:209] neg_lo:[0,1] neg_hi:[0,1]
	v_pk_add_f32 v[212:213], v[212:213], v[208:209] neg_lo:[0,1] neg_hi:[0,1]
	v_pk_add_f32 v[216:217], v[216:217], v[214:215] neg_lo:[0,1] neg_hi:[0,1]
	v_pk_add_f32 v[218:219], v[218:219], v[214:215] neg_lo:[0,1] neg_hi:[0,1]
	v_pk_fma_f32 v[196:197], v[198:199], v[18:19], v[196:197]
	v_pk_fma_f32 v[202:203], v[204:205], v[20:21], v[202:203]
	v_pk_fma_f32 v[208:209], v[210:211], v[22:23], v[208:209]
	v_pk_fma_f32 v[214:215], v[216:217], v[24:25], v[214:215]
	v_pk_fma_f32 v[196:197], v[200:201], v[26:27], v[196:197]
	v_pk_fma_f32 v[202:203], v[206:207], v[28:29], v[202:203]
	v_pk_fma_f32 v[208:209], v[212:213], v[30:31], v[208:209]
	v_pk_fma_f32 v[214:215], v[218:219], v[32:33], v[214:215]
	v_cvt_pk_bf16_f32 v70, v196, v197
	v_cvt_pk_bf16_f32 v71, v202, v203
	v_cvt_pk_bf16_f32 v72, v208, v209
	v_cvt_pk_bf16_f32 v73, v214, v215
	ds_write_b128 v237, v[70:73] offset:384
	s_waitcnt vmcnt(12)
	v_lshlrev_b32_e32 v196, 16, v74
	v_and_b32_e32 v197, 0xffff0000, v74
	v_lshlrev_b32_e32 v198, 16, v106
	v_and_b32_e32 v199, 0xffff0000, v106
	v_lshlrev_b32_e32 v200, 16, v138
	v_and_b32_e32 v201, 0xffff0000, v138
	v_lshlrev_b32_e32 v202, 16, v75
	v_and_b32_e32 v203, 0xffff0000, v75
	v_lshlrev_b32_e32 v204, 16, v107
	v_and_b32_e32 v205, 0xffff0000, v107
	v_lshlrev_b32_e32 v206, 16, v139
	v_and_b32_e32 v207, 0xffff0000, v139
	v_lshlrev_b32_e32 v208, 16, v76
	v_and_b32_e32 v209, 0xffff0000, v76
	v_lshlrev_b32_e32 v210, 16, v108
	v_and_b32_e32 v211, 0xffff0000, v108
	v_lshlrev_b32_e32 v212, 16, v140
	v_and_b32_e32 v213, 0xffff0000, v140
	v_lshlrev_b32_e32 v214, 16, v77
	v_and_b32_e32 v215, 0xffff0000, v77
	v_lshlrev_b32_e32 v216, 16, v109
	v_and_b32_e32 v217, 0xffff0000, v109
	v_lshlrev_b32_e32 v218, 16, v141
	v_and_b32_e32 v219, 0xffff0000, v141
	v_pk_add_f32 v[198:199], v[198:199], v[196:197] neg_lo:[0,1] neg_hi:[0,1]
	v_pk_add_f32 v[200:201], v[200:201], v[196:197] neg_lo:[0,1] neg_hi:[0,1]
	v_pk_add_f32 v[204:205], v[204:205], v[202:203] neg_lo:[0,1] neg_hi:[0,1]
	v_pk_add_f32 v[206:207], v[206:207], v[202:203] neg_lo:[0,1] neg_hi:[0,1]
	v_pk_add_f32 v[210:211], v[210:211], v[208:209] neg_lo:[0,1] neg_hi:[0,1]
	v_pk_add_f32 v[212:213], v[212:213], v[208:209] neg_lo:[0,1] neg_hi:[0,1]
	v_pk_add_f32 v[216:217], v[216:217], v[214:215] neg_lo:[0,1] neg_hi:[0,1]
	v_pk_add_f32 v[218:219], v[218:219], v[214:215] neg_lo:[0,1] neg_hi:[0,1]
	v_pk_fma_f32 v[196:197], v[198:199], v[34:35], v[196:197]
	v_pk_fma_f32 v[202:203], v[204:205], v[36:37], v[202:203]
	v_pk_fma_f32 v[208:209], v[210:211], v[38:39], v[208:209]
	v_pk_fma_f32 v[214:215], v[216:217], v[40:41], v[214:215]
	v_pk_fma_f32 v[196:197], v[200:201], v[42:43], v[196:197]
	v_pk_fma_f32 v[202:203], v[206:207], v[44:45], v[202:203]
	v_pk_fma_f32 v[208:209], v[212:213], v[46:47], v[208:209]
	v_pk_fma_f32 v[214:215], v[218:219], v[48:49], v[214:215]
	v_cvt_pk_bf16_f32 v74, v196, v197
	v_cvt_pk_bf16_f32 v75, v202, v203
	v_cvt_pk_bf16_f32 v76, v208, v209
	v_cvt_pk_bf16_f32 v77, v214, v215
	ds_write_b128 v237, v[74:77] offset:512
	s_waitcnt vmcnt(8)
	v_lshlrev_b32_e32 v196, 16, v78
	v_and_b32_e32 v197, 0xffff0000, v78
	v_lshlrev_b32_e32 v198, 16, v110
	v_and_b32_e32 v199, 0xffff0000, v110
	v_lshlrev_b32_e32 v200, 16, v142
	v_and_b32_e32 v201, 0xffff0000, v142
	v_lshlrev_b32_e32 v202, 16, v79
	v_and_b32_e32 v203, 0xffff0000, v79
	v_lshlrev_b32_e32 v204, 16, v111
	v_and_b32_e32 v205, 0xffff0000, v111
	v_lshlrev_b32_e32 v206, 16, v143
	v_and_b32_e32 v207, 0xffff0000, v143
	v_lshlrev_b32_e32 v208, 16, v80
	v_and_b32_e32 v209, 0xffff0000, v80
	v_lshlrev_b32_e32 v210, 16, v112
	v_and_b32_e32 v211, 0xffff0000, v112
	v_lshlrev_b32_e32 v212, 16, v144
	v_and_b32_e32 v213, 0xffff0000, v144
	v_lshlrev_b32_e32 v214, 16, v81
	v_and_b32_e32 v215, 0xffff0000, v81
	v_lshlrev_b32_e32 v216, 16, v113
	v_and_b32_e32 v217, 0xffff0000, v113
	v_lshlrev_b32_e32 v218, 16, v145
	v_and_b32_e32 v219, 0xffff0000, v145
	v_pk_add_f32 v[198:199], v[198:199], v[196:197] neg_lo:[0,1] neg_hi:[0,1]
	v_pk_add_f32 v[200:201], v[200:201], v[196:197] neg_lo:[0,1] neg_hi:[0,1]
	v_pk_add_f32 v[204:205], v[204:205], v[202:203] neg_lo:[0,1] neg_hi:[0,1]
	v_pk_add_f32 v[206:207], v[206:207], v[202:203] neg_lo:[0,1] neg_hi:[0,1]
	v_pk_add_f32 v[210:211], v[210:211], v[208:209] neg_lo:[0,1] neg_hi:[0,1]
	v_pk_add_f32 v[212:213], v[212:213], v[208:209] neg_lo:[0,1] neg_hi:[0,1]
	v_pk_add_f32 v[216:217], v[216:217], v[214:215] neg_lo:[0,1] neg_hi:[0,1]
	v_pk_add_f32 v[218:219], v[218:219], v[214:215] neg_lo:[0,1] neg_hi:[0,1]
	v_pk_fma_f32 v[196:197], v[198:199], v[154:155], v[196:197]
	v_pk_fma_f32 v[202:203], v[204:205], v[156:157], v[202:203]
	v_pk_fma_f32 v[208:209], v[210:211], v[158:159], v[208:209]
	v_pk_fma_f32 v[214:215], v[216:217], v[160:161], v[214:215]
	v_pk_fma_f32 v[196:197], v[200:201], v[162:163], v[196:197]
	v_pk_fma_f32 v[202:203], v[206:207], v[164:165], v[202:203]
	v_pk_fma_f32 v[208:209], v[212:213], v[166:167], v[208:209]
	v_pk_fma_f32 v[214:215], v[218:219], v[168:169], v[214:215]
	v_cvt_pk_bf16_f32 v78, v196, v197
	v_cvt_pk_bf16_f32 v79, v202, v203
	v_cvt_pk_bf16_f32 v80, v208, v209
	v_cvt_pk_bf16_f32 v81, v214, v215
	ds_write_b128 v237, v[78:81] offset:640
	s_waitcnt vmcnt(4)
	v_lshlrev_b32_e32 v196, 16, v82
	v_and_b32_e32 v197, 0xffff0000, v82
	v_lshlrev_b32_e32 v198, 16, v114
	v_and_b32_e32 v199, 0xffff0000, v114
	v_lshlrev_b32_e32 v200, 16, v146
	v_and_b32_e32 v201, 0xffff0000, v146
	v_lshlrev_b32_e32 v202, 16, v83
	v_and_b32_e32 v203, 0xffff0000, v83
	v_lshlrev_b32_e32 v204, 16, v115
	v_and_b32_e32 v205, 0xffff0000, v115
	v_lshlrev_b32_e32 v206, 16, v147
	v_and_b32_e32 v207, 0xffff0000, v147
	v_lshlrev_b32_e32 v208, 16, v84
	v_and_b32_e32 v209, 0xffff0000, v84
	v_lshlrev_b32_e32 v210, 16, v116
	v_and_b32_e32 v211, 0xffff0000, v116
	v_lshlrev_b32_e32 v212, 16, v148
	v_and_b32_e32 v213, 0xffff0000, v148
	v_lshlrev_b32_e32 v214, 16, v85
	v_and_b32_e32 v215, 0xffff0000, v85
	v_lshlrev_b32_e32 v216, 16, v117
	v_and_b32_e32 v217, 0xffff0000, v117
	v_lshlrev_b32_e32 v218, 16, v149
	v_and_b32_e32 v219, 0xffff0000, v149
	v_pk_add_f32 v[198:199], v[198:199], v[196:197] neg_lo:[0,1] neg_hi:[0,1]
	v_pk_add_f32 v[200:201], v[200:201], v[196:197] neg_lo:[0,1] neg_hi:[0,1]
	v_pk_add_f32 v[204:205], v[204:205], v[202:203] neg_lo:[0,1] neg_hi:[0,1]
	v_pk_add_f32 v[206:207], v[206:207], v[202:203] neg_lo:[0,1] neg_hi:[0,1]
	v_pk_add_f32 v[210:211], v[210:211], v[208:209] neg_lo:[0,1] neg_hi:[0,1]
	v_pk_add_f32 v[212:213], v[212:213], v[208:209] neg_lo:[0,1] neg_hi:[0,1]
	v_pk_add_f32 v[216:217], v[216:217], v[214:215] neg_lo:[0,1] neg_hi:[0,1]
	v_pk_add_f32 v[218:219], v[218:219], v[214:215] neg_lo:[0,1] neg_hi:[0,1]
	v_pk_fma_f32 v[196:197], v[198:199], v[170:171], v[196:197]
	v_pk_fma_f32 v[202:203], v[204:205], v[172:173], v[202:203]
	v_pk_fma_f32 v[208:209], v[210:211], v[174:175], v[208:209]
	v_pk_fma_f32 v[214:215], v[216:217], v[176:177], v[214:215]
	v_pk_fma_f32 v[196:197], v[200:201], v[178:179], v[196:197]
	v_pk_fma_f32 v[202:203], v[206:207], v[180:181], v[202:203]
	v_pk_fma_f32 v[208:209], v[212:213], v[182:183], v[208:209]
	v_pk_fma_f32 v[214:215], v[218:219], v[184:185], v[214:215]
	v_cvt_pk_bf16_f32 v82, v196, v197
	v_cvt_pk_bf16_f32 v83, v202, v203
	v_cvt_pk_bf16_f32 v84, v208, v209
	v_cvt_pk_bf16_f32 v85, v214, v215
	ds_write_b128 v237, v[82:85] offset:768
	s_waitcnt vmcnt(0)
	v_lshlrev_b32_e32 v196, 16, v86
	v_and_b32_e32 v197, 0xffff0000, v86
	v_lshlrev_b32_e32 v198, 16, v118
	v_and_b32_e32 v199, 0xffff0000, v118
	v_lshlrev_b32_e32 v200, 16, v150
	v_and_b32_e32 v201, 0xffff0000, v150
	v_lshlrev_b32_e32 v202, 16, v87
	v_and_b32_e32 v203, 0xffff0000, v87
	v_lshlrev_b32_e32 v204, 16, v119
	v_and_b32_e32 v205, 0xffff0000, v119
	v_lshlrev_b32_e32 v206, 16, v151
	v_and_b32_e32 v207, 0xffff0000, v151
	v_lshlrev_b32_e32 v208, 16, v88
	v_and_b32_e32 v209, 0xffff0000, v88
	v_lshlrev_b32_e32 v210, 16, v120
	v_and_b32_e32 v211, 0xffff0000, v120
	v_lshlrev_b32_e32 v212, 16, v152
	v_and_b32_e32 v213, 0xffff0000, v152
	v_lshlrev_b32_e32 v214, 16, v89
	v_and_b32_e32 v215, 0xffff0000, v89
	v_lshlrev_b32_e32 v216, 16, v121
	v_and_b32_e32 v217, 0xffff0000, v121
	v_lshlrev_b32_e32 v218, 16, v153
	v_and_b32_e32 v219, 0xffff0000, v153
	v_pk_add_f32 v[198:199], v[198:199], v[196:197] neg_lo:[0,1] neg_hi:[0,1]
	v_pk_add_f32 v[200:201], v[200:201], v[196:197] neg_lo:[0,1] neg_hi:[0,1]
	v_pk_add_f32 v[204:205], v[204:205], v[202:203] neg_lo:[0,1] neg_hi:[0,1]
	v_pk_add_f32 v[206:207], v[206:207], v[202:203] neg_lo:[0,1] neg_hi:[0,1]
	v_pk_add_f32 v[210:211], v[210:211], v[208:209] neg_lo:[0,1] neg_hi:[0,1]
	v_pk_add_f32 v[212:213], v[212:213], v[208:209] neg_lo:[0,1] neg_hi:[0,1]
	v_pk_add_f32 v[216:217], v[216:217], v[214:215] neg_lo:[0,1] neg_hi:[0,1]
	v_pk_add_f32 v[218:219], v[218:219], v[214:215] neg_lo:[0,1] neg_hi:[0,1]
	v_pk_fma_f32 v[196:197], v[198:199], v[90:91], v[196:197]
	v_pk_fma_f32 v[202:203], v[204:205], v[92:93], v[202:203]
	v_pk_fma_f32 v[208:209], v[210:211], v[94:95], v[208:209]
	v_pk_fma_f32 v[214:215], v[216:217], v[96:97], v[214:215]
	v_pk_fma_f32 v[196:197], v[200:201], v[122:123], v[196:197]
	v_pk_fma_f32 v[202:203], v[206:207], v[124:125], v[202:203]
	v_pk_fma_f32 v[208:209], v[212:213], v[126:127], v[208:209]
	v_pk_fma_f32 v[214:215], v[218:219], v[128:129], v[214:215]
	v_cvt_pk_bf16_f32 v86, v196, v197
	v_cvt_pk_bf16_f32 v87, v202, v203
	v_cvt_pk_bf16_f32 v88, v208, v209
	v_cvt_pk_bf16_f32 v89, v214, v215
	ds_write_b128 v237, v[86:89] offset:896

.LBB0_472:
	s_lshl_b64 s[28:29], s[38:39], 15
	s_waitcnt lgkmcnt(0)
	s_add_u32 s3, s36, s28
	v_ashrrev_i32_e32 v152, 5, v150
	s_addc_u32 s37, s37, s29
	s_lshl_b64 s[28:29], s[30:31], 13
	v_and_b32_e32 v151, 31, v150
	v_lshlrev_b32_e32 v153, 4, v152
	s_add_u32 s38, s68, s28
	s_addc_u32 s39, s69, s29
	v_lshl_add_u32 v130, v151, 5, v153
	s_add_u32 s28, s3, 0x6000
	v_add_u32_e32 v2, 0xc00, v130
	s_addc_u32 s29, s37, 0
	v_ashrrev_i32_e32 v3, 31, v2
	v_lshl_add_u64 v[6:7], v[2:3], 1, s[28:29]
	global_load_dwordx4 v[2:5], v[6:7], off offset:16 nt
	s_nop 0
	global_load_dwordx4 v[6:9], v[6:7], off nt
	v_ashrrev_i32_e32 v131, 31, v130
	v_lshlrev_b64 v[132:133], 1, v[130:131]
	v_lshl_add_u64 v[54:55], s[28:29], 0, v[132:133]
	v_lshlrev_b32_e32 v134, 3, v150
	s_add_u32 s36, s3, 0x2000
	v_lshl_add_u64 v[94:95], s[38:39], 0, v[132:133]
	v_add_u32_e32 v136, 0x200, v134
	v_add_u32_e32 v138, 0x400, v134
	v_add_u32_e32 v140, 0x600, v134
	s_movk_i32 s3, 0x1000
	v_add_u32_e32 v142, 0x800, v134
	s_addc_u32 s37, s37, 0
	v_ashrrev_i32_e32 v135, 31, v134
	v_ashrrev_i32_e32 v137, 31, v136
	v_ashrrev_i32_e32 v139, 31, v138
	v_ashrrev_i32_e32 v141, 31, v140
	v_add_co_u32_e32 v106, vcc, s3, v94
	v_ashrrev_i32_e32 v143, 31, v142
	v_add_u32_e32 v144, 0xa00, v134
	v_lshl_add_u64 v[74:75], v[134:135], 1, s[36:37]
	v_lshl_add_u64 v[78:79], v[136:137], 1, s[36:37]
	v_lshl_add_u64 v[90:91], v[138:139], 1, s[36:37]
	v_lshl_add_u64 v[96:97], v[140:141], 1, s[36:37]
	v_addc_co_u32_e32 v107, vcc, 0, v95, vcc
	v_lshl_add_u64 v[108:109], v[142:143], 1, s[36:37]
	v_ashrrev_i32_e32 v145, 31, v144
	v_add_u32_e32 v146, 0xc00, v134
	v_add_u32_e32 v148, 0xe00, v134
	v_ashrrev_i32_e32 v147, 31, v146
	v_ashrrev_i32_e32 v149, 31, v148
	v_lshl_add_u64 v[122:123], v[146:147], 1, s[36:37]
	v_lshl_add_u64 v[126:127], v[148:149], 1, s[36:37]
	s_waitcnt vmcnt(1)
	v_cvt_f32_f16_e32 v10, v2
	s_waitcnt vmcnt(0)
	v_cvt_f32_f16_e32 v18, v6
	v_cvt_f32_f16_sdwa v19, v6 dst_sel:DWORD dst_unused:UNUSED_PAD src0_sel:WORD_1
	v_cvt_f32_f16_sdwa v11, v2 dst_sel:DWORD dst_unused:UNUSED_PAD src0_sel:WORD_1
	v_cvt_f32_f16_e32 v2, v3
	v_cvt_f32_f16_sdwa v3, v3 dst_sel:DWORD dst_unused:UNUSED_PAD src0_sel:WORD_1
	v_cvt_f32_f16_e32 v12, v4
	v_cvt_f32_f16_sdwa v13, v4 dst_sel:DWORD dst_unused:UNUSED_PAD src0_sel:WORD_1
	v_cvt_f32_f16_e32 v20, v7
	v_cvt_f32_f16_sdwa v21, v7 dst_sel:DWORD dst_unused:UNUSED_PAD src0_sel:WORD_1
	v_cvt_f32_f16_e32 v4, v5
	v_cvt_f32_f16_sdwa v5, v5 dst_sel:DWORD dst_unused:UNUSED_PAD src0_sel:WORD_1
	v_pk_add_f32 v[14:15], v[12:13], 0 op_sel_hi:[1,0]
	v_pk_add_f32 v[12:13], v[2:3], 0 op_sel_hi:[1,0]
	v_pk_add_f32 v[2:3], v[18:19], 0 op_sel_hi:[1,0]
	v_add_u32_e32 v18, 0x400, v130
	v_ashrrev_i32_e32 v19, 31, v18
	v_lshl_add_u64 v[22:23], v[18:19], 1, s[28:29]
	v_pk_add_f32 v[16:17], v[4:5], 0 op_sel_hi:[1,0]
	v_pk_add_f32 v[4:5], v[20:21], 0 op_sel_hi:[1,0]
	global_load_dwordx4 v[18:21], v[22:23], off offset:16 nt
	s_nop 0
	global_load_dwordx4 v[22:25], v[22:23], off nt
	v_cvt_f32_f16_e32 v6, v8
	v_cvt_f32_f16_sdwa v7, v8 dst_sel:DWORD dst_unused:UNUSED_PAD src0_sel:WORD_1
	v_cvt_f32_f16_e32 v8, v9
	v_cvt_f32_f16_sdwa v9, v9 dst_sel:DWORD dst_unused:UNUSED_PAD src0_sel:WORD_1
	v_pk_add_f32 v[10:11], v[10:11], 0 op_sel_hi:[1,0]
	v_pk_add_f32 v[6:7], v[6:7], 0 op_sel_hi:[1,0]
	v_pk_add_f32 v[8:9], v[8:9], 0 op_sel_hi:[1,0]
	s_waitcnt vmcnt(1)
	v_cvt_f32_f16_e32 v26, v18
	s_waitcnt vmcnt(0)
	v_cvt_f32_f16_e32 v34, v22
	v_cvt_f32_f16_sdwa v35, v22 dst_sel:DWORD dst_unused:UNUSED_PAD src0_sel:WORD_1
	v_cvt_f32_f16_sdwa v27, v18 dst_sel:DWORD dst_unused:UNUSED_PAD src0_sel:WORD_1
	v_cvt_f32_f16_e32 v18, v19
	v_cvt_f32_f16_sdwa v19, v19 dst_sel:DWORD dst_unused:UNUSED_PAD src0_sel:WORD_1
	v_cvt_f32_f16_e32 v28, v20
	v_cvt_f32_f16_sdwa v29, v20 dst_sel:DWORD dst_unused:UNUSED_PAD src0_sel:WORD_1
	v_cvt_f32_f16_e32 v36, v23
	v_cvt_f32_f16_sdwa v37, v23 dst_sel:DWORD dst_unused:UNUSED_PAD src0_sel:WORD_1
	v_cvt_f32_f16_e32 v20, v21
	v_cvt_f32_f16_sdwa v21, v21 dst_sel:DWORD dst_unused:UNUSED_PAD src0_sel:WORD_1
	v_pk_add_f32 v[30:31], v[28:29], 0 op_sel_hi:[1,0]
	v_pk_add_f32 v[28:29], v[18:19], 0 op_sel_hi:[1,0]
	v_pk_add_f32 v[18:19], v[34:35], 0 op_sel_hi:[1,0]
	v_add_u32_e32 v34, 0x800, v130
	v_ashrrev_i32_e32 v35, 31, v34
	v_lshl_add_u64 v[38:39], v[34:35], 1, s[28:29]
	v_pk_add_f32 v[32:33], v[20:21], 0 op_sel_hi:[1,0]
	v_pk_add_f32 v[20:21], v[36:37], 0 op_sel_hi:[1,0]
	global_load_dwordx4 v[34:37], v[38:39], off offset:16 nt
	s_nop 0
	global_load_dwordx4 v[38:41], v[38:39], off nt
	v_cvt_f32_f16_e32 v22, v24
	v_cvt_f32_f16_sdwa v23, v24 dst_sel:DWORD dst_unused:UNUSED_PAD src0_sel:WORD_1
	v_cvt_f32_f16_e32 v24, v25
	v_cvt_f32_f16_sdwa v25, v25 dst_sel:DWORD dst_unused:UNUSED_PAD src0_sel:WORD_1
	v_pk_add_f32 v[26:27], v[26:27], 0 op_sel_hi:[1,0]
	v_pk_add_f32 v[22:23], v[22:23], 0 op_sel_hi:[1,0]
	v_pk_add_f32 v[24:25], v[24:25], 0 op_sel_hi:[1,0]
	s_waitcnt vmcnt(1)
	v_cvt_f32_f16_e32 v42, v34
	s_waitcnt vmcnt(0)
	v_cvt_f32_f16_e32 v50, v38
	v_cvt_f32_f16_sdwa v51, v38 dst_sel:DWORD dst_unused:UNUSED_PAD src0_sel:WORD_1
	v_cvt_f32_f16_e32 v52, v39
	v_cvt_f32_f16_sdwa v53, v39 dst_sel:DWORD dst_unused:UNUSED_PAD src0_sel:WORD_1
	v_cvt_f32_f16_sdwa v43, v34 dst_sel:DWORD dst_unused:UNUSED_PAD src0_sel:WORD_1
	v_cvt_f32_f16_e32 v34, v35
	v_cvt_f32_f16_sdwa v35, v35 dst_sel:DWORD dst_unused:UNUSED_PAD src0_sel:WORD_1
	v_cvt_f32_f16_e32 v44, v36
	v_cvt_f32_f16_sdwa v45, v36 dst_sel:DWORD dst_unused:UNUSED_PAD src0_sel:WORD_1
	v_cvt_f32_f16_e32 v36, v37
	v_cvt_f32_f16_sdwa v37, v37 dst_sel:DWORD dst_unused:UNUSED_PAD src0_sel:WORD_1
	v_cvt_f32_f16_e32 v38, v40
	v_pk_add_f32 v[46:47], v[44:45], 0 op_sel_hi:[1,0]
	v_pk_add_f32 v[44:45], v[34:35], 0 op_sel_hi:[1,0]
	v_pk_add_f32 v[48:49], v[36:37], 0 op_sel_hi:[1,0]
	v_pk_add_f32 v[36:37], v[52:53], 0 op_sel_hi:[1,0]
	v_pk_add_f32 v[34:35], v[50:51], 0 op_sel_hi:[1,0]
	global_load_dwordx4 v[50:53], v[54:55], off offset:16 nt
	s_nop 0
	global_load_dwordx4 v[54:57], v[54:55], off nt
	v_cvt_f32_f16_sdwa v39, v40 dst_sel:DWORD dst_unused:UNUSED_PAD src0_sel:WORD_1
	v_cvt_f32_f16_e32 v40, v41
	v_cvt_f32_f16_sdwa v41, v41 dst_sel:DWORD dst_unused:UNUSED_PAD src0_sel:WORD_1
	v_pk_add_f32 v[42:43], v[42:43], 0 op_sel_hi:[1,0]
	v_pk_add_f32 v[38:39], v[38:39], 0 op_sel_hi:[1,0]
	v_pk_add_f32 v[40:41], v[40:41], 0 op_sel_hi:[1,0]
	s_waitcnt vmcnt(1)
	v_cvt_f32_f16_e32 v58, v50
	s_waitcnt vmcnt(0)
	v_cvt_f32_f16_e32 v66, v54
	v_cvt_f32_f16_sdwa v67, v54 dst_sel:DWORD dst_unused:UNUSED_PAD src0_sel:WORD_1
	v_cvt_f32_f16_e32 v68, v55
	v_cvt_f32_f16_sdwa v69, v55 dst_sel:DWORD dst_unused:UNUSED_PAD src0_sel:WORD_1
	v_cvt_f32_f16_sdwa v59, v50 dst_sel:DWORD dst_unused:UNUSED_PAD src0_sel:WORD_1
	v_cvt_f32_f16_e32 v50, v51
	v_cvt_f32_f16_sdwa v51, v51 dst_sel:DWORD dst_unused:UNUSED_PAD src0_sel:WORD_1
	v_cvt_f32_f16_e32 v60, v52
	v_cvt_f32_f16_sdwa v61, v52 dst_sel:DWORD dst_unused:UNUSED_PAD src0_sel:WORD_1
	v_cvt_f32_f16_e32 v52, v53
	v_cvt_f32_f16_sdwa v53, v53 dst_sel:DWORD dst_unused:UNUSED_PAD src0_sel:WORD_1
	v_cvt_f32_f16_e32 v54, v56
	v_pk_add_f32 v[62:63], v[60:61], 0 op_sel_hi:[1,0]
	v_pk_add_f32 v[60:61], v[50:51], 0 op_sel_hi:[1,0]
	v_pk_add_f32 v[64:65], v[52:53], 0 op_sel_hi:[1,0]
	v_pk_add_f32 v[52:53], v[68:69], 0 op_sel_hi:[1,0]
	v_pk_add_f32 v[50:51], v[66:67], 0 op_sel_hi:[1,0]
	global_load_dwordx4 v[70:73], v[94:95], off nt
	global_load_dwordx4 v[66:69], v[94:95], off offset:2048 nt
	v_cvt_f32_f16_sdwa v55, v56 dst_sel:DWORD dst_unused:UNUSED_PAD src0_sel:WORD_1
	global_load_dwordx4 v[74:77], v[74:75], off nt
	s_nop 0
	global_load_dwordx4 v[86:89], v[78:79], off nt
	global_load_dwordx4 v[82:85], v[94:95], off offset:16 nt
	s_nop 0
	global_load_dwordx4 v[78:81], v[94:95], off offset:2064 nt
	global_load_dwordx4 v[102:105], v[96:97], off nt
	v_cvt_f32_f16_e32 v56, v57
	global_load_dwordx4 v[90:93], v[90:91], off nt
	s_nop 0
	global_load_dwordx4 v[98:101], v[106:107], off nt
	global_load_dwordx4 v[94:97], v[106:107], off offset:2048 nt
	global_load_dwordx4 v[110:113], v[108:109], off nt
	v_lshl_add_u64 v[108:109], v[144:145], 1, s[36:37]
	global_load_dwordx4 v[118:121], v[108:109], off nt
	global_load_dwordx4 v[114:117], v[106:107], off offset:16 nt
	s_nop 0
	global_load_dwordx4 v[106:109], v[106:107], off offset:2064 nt
	v_cvt_f32_f16_sdwa v57, v57 dst_sel:DWORD dst_unused:UNUSED_PAD src0_sel:WORD_1
	global_load_dwordx4 v[122:125], v[122:123], off nt
	v_pk_add_f32 v[58:59], v[58:59], 0 op_sel_hi:[1,0]
	global_load_dwordx4 v[126:129], v[126:127], off nt
	v_pk_add_f32 v[56:57], v[56:57], 0 op_sel_hi:[1,0]
	v_pk_add_f32 v[54:55], v[54:55], 0 op_sel_hi:[1,0]
	s_waitcnt vmcnt(13)
	s_nop 0
	v_mfma_f32_32x32x16_f16 v[50:65], v[70:73], v[74:77], v[50:65]
	s_xor_b32 s30, s30, 0x7f
	s_ashr_i32 s31, s30, 31
	s_cmpk_lt_i32 s30, 0x800
	s_mov_b64 s[38:39], s[30:31]
	s_mov_b64 s[36:37], s[26:27]
	v_mfma_f32_32x32x16_f16 v[34:49], v[66:69], v[74:77], v[34:49]
	s_waitcnt vmcnt(12)
	v_mfma_f32_32x32x16_f16 v[18:33], v[70:73], v[86:89], v[18:33]
	v_mfma_f32_32x32x16_f16 v[2:17], v[66:69], v[86:89], v[2:17]
	s_waitcnt vmcnt(8)
	v_mfma_f32_32x32x16_f16 v[50:65], v[82:85], v[90:93], v[50:65]
	v_mfma_f32_32x32x16_f16 v[34:49], v[78:81], v[90:93], v[34:49]
	v_mfma_f32_32x32x16_f16 v[18:33], v[82:85], v[102:105], v[18:33]
	v_mfma_f32_32x32x16_f16 v[2:17], v[78:81], v[102:105], v[2:17]
	s_waitcnt vmcnt(5)
	v_mfma_f32_32x32x16_f16 v[50:65], v[98:101], v[110:113], v[50:65]
	v_mfma_f32_32x32x16_f16 v[34:49], v[94:97], v[110:113], v[34:49]
	s_waitcnt vmcnt(4)
	v_mfma_f32_32x32x16_f16 v[18:33], v[98:101], v[118:121], v[18:33]
	v_mfma_f32_32x32x16_f16 v[2:17], v[94:97], v[118:121], v[2:17]
	s_waitcnt vmcnt(1)
	v_mfma_f32_32x32x16_f16 v[50:65], v[114:117], v[122:125], v[50:65]
	v_mfma_f32_32x32x16_f16 v[34:49], v[106:109], v[122:125], v[34:49]
	s_waitcnt vmcnt(0)
	v_mfma_f32_32x32x16_f16 v[18:33], v[114:117], v[126:129], v[18:33]
	v_mfma_f32_32x32x16_f16 v[2:17], v[106:109], v[126:129], v[2:17]
	s_cbranch_scc1 .LBB0_451
	v_readlane_b32 s28, v254, 59
	v_readlane_b32 s29, v254, 60
	s_load_dwordx2 s[36:37], s[28:29], 0xa8
	s_add_i32 s50, s30, 0xfffff800
	s_mov_b64 s[38:39], s[50:51]
	s_branch .LBB0_451
	s_nop 0
	s_nop 0
	s_nop 0
	s_nop 0
	s_nop 0
	s_nop 0
	s_nop 0
	s_nop 0
	s_nop 0
	s_nop 0
	s_nop 0
	s_nop 0
	s_nop 0
